# wkv chunk-record stores (190 MB per layer, read by other CUs next phase) marked non-temporal so they do not evict the phase's L2-resident inputs
# speedup vs baseline: 1.0038x; 1.0038x over previous
; __device__ __forceinline__ v2u pk4(const f32x4 v) { return __builtin_bit_cast(v2u, __builtin_convertvector(v, bf4v)); }
; __device__ __forceinline__ f32x4 mm16(const v2u a, const v2u b, const f32x4 c) { return __builtin_amdgcn_mfma_f32_16x16x16bf16_1k(__builtin_bit_cast(v4s, a), __builtin_bit_cast(v4s, b), c, 0, 0, 0); }
; __device__ __forceinline__ void ph_wkv1(const Params& p, int jl, LAS unsigned char* lds, int lane_in, int wave) {
;     ...
;         const f32x4 z4 = (f32x4){0.f, 0.f, 0.f, 0.f};
;         const int dd = fr - 4 * fq;
;         f32x4 L = mm32(pa[2], pa[3], pb[2], pb[3], mm32(pa[0], pa[1], pb[0], pb[1], z4));
;         f32x4 LT = mm32(pb[2], pb[3], pa[2], pa[3], mm32(pb[0], pb[1], pa[0], pa[1], z4));
;         f32x4 Lak = mm32(pa[2], pa[3], pk[2], pk[3], mm32(pa[0], pa[1], pk[0], pk[1], z4));
;         f32x4 MrbT = mm32(pb[2], pb[3], pr[2], pr[3], mm32(pb[0], pb[1], pr[0], pr[1], z4));
;         f32x4 MrkT = mm32(pk[2], pk[3], pr[2], pr[3], mm32(pk[0], pk[1], pr[0], pr[1], z4));
;         f32x4 TT;
; #pragma unroll
;         for (int r = 0; r < 4; ++r) {
;             L[r] = dd < r ? L[r] : 0.f; Lak[r] = dd < r ? Lak[r] : 0.f;
;             LT[r] = r < dd ? LT[r] : 0.f; MrbT[r] = r <= dd ? MrbT[r] : 0.f; MrkT[r] = r <= dd ? MrkT[r] : 0.f;
;             TT[r] = LT[r] + (r == dd ? 1.f : 0.f);
;         }
;         const v2u bL = pk4(L), bLT = pk4(LT), bLak = pk4(Lak);
;         const f32x4 L2m = mm16(bLT, bL, z4), L2T = mm16(bL, bLT, z4);
;         const v2u bL2 = pk4(L2m), bL2T = pk4(L2T);
;         const f32x4 L4m = mm16(bL2T, bL2, z4), L4T = mm16(bL2, bL2T, z4);
;         const v2u bL4 = pk4(L4m), bL4T = pk4(L4T);
;         const v2u bL8 = pk4(mm16(bL4T, bL4, z4));
;         TT = mm16(bL2, pk4(TT), TT); TT = mm16(bL4, pk4(TT), TT); TT = mm16(bL8, pk4(TT), TT);
;         f32x4 Zm = mm16(bL, pk4(MrbT), MrbT); Zm = mm16(bL2, pk4(Zm), Zm); Zm = mm16(bL4, pk4(Zm), Zm); Zm = mm16(bL8, pk4(Zm), Zm);
;         const v2u bTT = pk4(TT), bMtT = pk4(Zm);
.LBB0_198:
	s_or_b64 exec, exec, s[0:1]
	s_waitcnt lgkmcnt(0)
	v_pk_mul_f32 v[60:61], v[88:89], v[64:65]
	v_pk_mul_f32 v[62:63], v[90:91], v[66:67]
	v_pk_mul_f32 v[64:65], v[92:93], v[68:69]
	v_pk_mul_f32 v[66:67], v[94:95], v[70:71]
	v_pk_mul_f32 v[68:69], v[96:97], v[72:73]
	v_pk_mul_f32 v[70:71], v[98:99], v[74:75]
	v_pk_mul_f32 v[72:73], v[100:101], v[116:117]
	v_pk_mul_f32 v[74:75], v[102:103], v[118:119]
	v_cvt_pk_bf16_f32 v95, v70, v71
	v_cvt_pk_bf16_f32 v94, v68, v69
	v_cvt_pk_bf16_f32 v93, v74, v75
	v_cvt_pk_bf16_f32 v92, v72, v73
	v_mfma_f32_16x16x32_bf16 v[96:99], v[84:87], v[80:83], 0
	v_cvt_pk_bf16_f32 v91, v62, v63
	v_cvt_pk_bf16_f32 v90, v60, v61
	v_cvt_pk_bf16_f32 v89, v66, v67
	v_mfma_f32_16x16x32_bf16 v[100:103], v[80:83], v[84:87], 0
	v_cvt_pk_bf16_f32 v88, v64, v65
	v_sub_u32_e32 v0, v166, v165
	v_cmp_gt_i32_e32 vcc, 0, v0
	v_mfma_f32_16x16x32_bf16 v[84:87], v[84:87], v[76:79], 0
	v_cmp_lt_i32_e64 s[0:1], 1, v0
	s_mov_b32 s20, s22
	v_mfma_f32_16x16x32_bf16 v[80:83], v[80:83], v[92:95], 0
	v_mfma_f32_16x16x32_bf16 v[76:79], v[76:79], v[92:95], 0
	v_mfma_f32_16x16x32_bf16 v[96:99], v[112:115], v[108:111], v[96:99]
	v_mfma_f32_16x16x32_bf16 v[84:87], v[112:115], v[104:107], v[84:87]
	v_mfma_f32_16x16x32_bf16 v[80:83], v[108:111], v[88:91], v[80:83]
	v_mfma_f32_16x16x32_bf16 v[76:79], v[104:107], v[88:91], v[76:79]
	s_nop 4
	v_cndmask_b32_e32 v90, 0, v96, vcc
	v_cndmask_b32_e32 v91, 0, v84, vcc
	v_cndmask_b32_e64 v80, v80, 0, vcc
	v_mfma_f32_16x16x32_bf16 v[100:103], v[108:111], v[112:115], v[100:103]
	v_cndmask_b32_e64 v76, v76, 0, vcc
	v_cmp_gt_i32_e32 vcc, 1, v0
	s_nop 5
	v_cndmask_b32_e64 v3, 0, v101, s[0:1]
	v_cmp_eq_u32_e64 s[0:1], v166, v165
	v_cndmask_b32_e32 v92, 0, v97, vcc
	v_cndmask_b32_e32 v93, 0, v85, vcc
	v_cndmask_b32_e64 v81, v81, 0, vcc
	v_cndmask_b32_e64 v77, v77, 0, vcc
	v_cmp_lt_i32_e32 vcc, 0, v0
	v_cndmask_b32_e64 v84, 0, 1.0, s[0:1]
	v_cmp_lt_i32_e64 s[0:1], 3, v0
	v_cndmask_b32_e32 v2, 0, v100, vcc
	v_cmp_eq_u32_e32 vcc, 1, v0
	v_cndmask_b32_e64 v89, 0, v103, s[0:1]
	v_cmp_eq_u32_e64 s[0:1], 3, v0
	v_cndmask_b32_e64 v85, 0, 1.0, vcc
	v_cmp_gt_i32_e32 vcc, 2, v0
	v_pk_add_f32 v[84:85], v[84:85], v[2:3]
	v_cvt_pk_bf16_f32 v2, v2, s0
	v_cndmask_b32_e32 v94, 0, v98, vcc
	v_cndmask_b32_e32 v95, 0, v86, vcc
	v_cndmask_b32_e64 v82, v82, 0, vcc
	v_cndmask_b32_e64 v78, v78, 0, vcc
	v_cmp_gt_i32_e32 vcc, 3, v0
	v_cvt_pk_bf16_f32 v100, v91, s0
	v_cvt_pk_bf16_f32 v101, v93, s0
	v_cndmask_b32_e32 v96, 0, v99, vcc
	v_cndmask_b32_e32 v97, 0, v87, vcc
	v_cndmask_b32_e64 v83, v83, 0, vcc
	v_cndmask_b32_e64 v79, v79, 0, vcc
	v_cmp_lt_i32_e32 vcc, 2, v0
	v_cndmask_b32_e64 v87, 0, 1.0, s[0:1]
	v_cvt_pk_bf16_f32 v103, v97, s0
	v_cndmask_b32_e32 v88, 0, v102, vcc
	v_cmp_eq_u32_e32 vcc, 2, v0
	v_cvt_pk_bf16_f32 v0, v90, s0
	v_cvt_pk_bf16_f32 v90, v92, s0
	v_cndmask_b32_e64 v86, 0, 1.0, vcc
	v_pk_add_f32 v[86:87], v[86:87], v[88:89]
	v_cvt_pk_bf16_f32 v92, v94, s0
	v_cvt_pk_bf16_f32 v94, v96, s0
	v_cvt_pk_bf16_f32 v96, v3, s0
	v_cvt_pk_bf16_f32 v3, v88, s0
	v_cvt_pk_bf16_f32 v88, v89, s0
	v_cvt_pk_bf16_f32 v102, v95, s0
	s_mov_b32 s0, 0x5040100
	v_perm_b32 v3, v88, v3, s0
	v_perm_b32 v2, v96, v2, s0
	v_perm_b32 v97, v94, v92, s0
	v_perm_b32 v96, v90, v0, s0
	s_nop 1
	v_mfma_f32_16x16x16_bf16 v[88:91], v[2:3], v[96:97], 0
	v_mfma_f32_16x16x16_bf16 v[92:95], v[96:97], v[2:3], 0
	s_nop 6
	v_cvt_pk_bf16_f32 v0, v88, s0
	v_cvt_pk_bf16_f32 v88, v89, s0
	v_cvt_pk_bf16_f32 v89, v90, s0
	v_cvt_pk_bf16_f32 v90, v91, s0
	v_cvt_pk_bf16_f32 v2, v92, s0
	v_cvt_pk_bf16_f32 v91, v93, s0
	v_cvt_pk_bf16_f32 v3, v94, s0
	v_cvt_pk_bf16_f32 v92, v95, s0
	v_perm_b32 v3, v92, v3, s0
	v_perm_b32 v2, v91, v2, s0
	v_perm_b32 v99, v90, v89, s0
	v_perm_b32 v98, v88, v0, s0
	s_nop 1
	v_mfma_f32_16x16x16_bf16 v[88:91], v[2:3], v[98:99], 0
	v_mfma_f32_16x16x16_bf16 v[92:95], v[98:99], v[2:3], 0
	s_nop 6
	v_cvt_pk_bf16_f32 v0, v88, s0
	v_cvt_pk_bf16_f32 v88, v89, s0
	v_cvt_pk_bf16_f32 v89, v90, s0
	v_cvt_pk_bf16_f32 v90, v91, s0
	v_cvt_pk_bf16_f32 v2, v92, s0
	v_cvt_pk_bf16_f32 v91, v93, s0
	v_cvt_pk_bf16_f32 v3, v94, s0
	v_cvt_pk_bf16_f32 v92, v95, s0
	v_perm_b32 v3, v92, v3, s0
	v_perm_b32 v2, v91, v2, s0
	v_perm_b32 v93, v90, v89, s0
	v_perm_b32 v92, v88, v0, s0
	v_cvt_pk_bf16_f32 v94, v87, s0
	s_nop 0
	v_mfma_f32_16x16x16_bf16 v[88:91], v[2:3], v[92:93], 0
	v_cvt_pk_bf16_f32 v2, v84, s0
	v_cvt_pk_bf16_f32 v3, v86, s0
	v_perm_b32 v3, v94, v3, s0
	s_nop 4
	v_cvt_pk_bf16_f32 v0, v88, s0
	v_cvt_pk_bf16_f32 v88, v89, s0
	v_cvt_pk_bf16_f32 v89, v90, s0
	v_cvt_pk_bf16_f32 v90, v91, s0
	v_cvt_pk_bf16_f32 v91, v85, s0
	v_perm_b32 v2, v91, v2, s0
	s_nop 1
	v_mfma_f32_16x16x16_bf16 v[84:87], v[98:99], v[2:3], v[84:87]
	s_nop 7
	v_cvt_pk_bf16_f32 v2, v84, s0
	v_cvt_pk_bf16_f32 v91, v85, s0
	v_cvt_pk_bf16_f32 v3, v86, s0
	v_cvt_pk_bf16_f32 v94, v87, s0
	v_perm_b32 v3, v94, v3, s0
	v_perm_b32 v2, v91, v2, s0
	s_nop 1
	v_mfma_f32_16x16x16_bf16 v[84:87], v[92:93], v[2:3], v[84:87]
	v_perm_b32 v3, v90, v89, s0
	v_perm_b32 v2, v88, v0, s0
	v_cvt_pk_bf16_f32 v0, v80, s0
	v_cvt_pk_bf16_f32 v90, v83, s0
	s_nop 3
	v_cvt_pk_bf16_f32 v91, v84, s0
	v_cvt_pk_bf16_f32 v94, v85, s0
	v_cvt_pk_bf16_f32 v95, v86, s0
	v_cvt_pk_bf16_f32 v104, v87, s0
	v_perm_b32 v89, v104, v95, s0
	v_perm_b32 v88, v94, v91, s0
	s_nop 1
	v_mfma_f32_16x16x16_bf16 v[84:87], v[2:3], v[88:89], v[84:87]
	v_cvt_pk_bf16_f32 v88, v81, s0
	v_cvt_pk_bf16_f32 v89, v82, s0
	v_perm_b32 v89, v90, v89, s0
	v_perm_b32 v88, v88, v0, s0
	s_nop 1
	v_mfma_f32_16x16x16_bf16 v[80:83], v[96:97], v[88:89], v[80:83]
	s_nop 7
; #define LAS __attribute__((address_space(3)))
; __device__ __forceinline__ v2u pk4(const f32x4 v) { return __builtin_bit_cast(v2u, __builtin_convertvector(v, bf4v)); }
; __device__ __forceinline__ f32x4 mm16(const v2u a, const v2u b, const f32x4 c) { return __builtin_amdgcn_mfma_f32_16x16x16bf16_1k(__builtin_bit_cast(v4s, a), __builtin_bit_cast(v4s, b), c, 0, 0, 0); }
; __device__ __forceinline__ v2u tr16(LAS unsigned char* a) { return __builtin_bit_cast(v2u, __builtin_amdgcn_ds_read_tr16_b64_v4i16((LAS v4s*)a)); }
; __device__ __forceinline__ void ph_wkv1(const Params& p, int jl, LAS unsigned char* lds, int lane_in, int wave) {
;     ...
;         { const v2u pTK = pk4(mm16(bLak, bTT, z4)), pMY = pk4(mm16(bLak, bMtT, MrkT)); *(v4u*)(rec + REC_TK + lane * 16) = (v4u){pTK.x, pTK.y, pMY.x, pMY.y}; }
;         LAS unsigned char* ir = sc + (4 * fq + ((lane & 15) >> 2)) * 144 + 8 * (lane & 3);
;         v2u wat[4], rpt[4];
; #pragma unroll
;         for (int jt = 0; jt < 4; ++jt) {
;             const v2u Qa = tr16(ir + 0 * IMG + 32 * jt), Qb = tr16(ir + 1 * IMG + 32 * jt), Qk = tr16(ir + 2 * IMG + 32 * jt);
;             wat[jt] = pk4(mm16(Qa, bTT, z4)); rpt[jt] = pk4(mm16(Qa, bMtT, rt[jt]));
;             *(v4u*)(rec + REC_BK + (jt * 64 + lane) * 16) = (v4u){Qb.x, Qb.y, Qk.x, Qk.y};
;         }
; #pragma unroll
;         for (int s = 0; s < 2; ++s) {
;             *(v4u*)(rec + REC_WA + (s * 64 + lane) * 16) = (v4u){wat[2 * s].x, wat[2 * s].y, wat[2 * s + 1].x, wat[2 * s + 1].y};
;             *(v4u*)(rec + REC_RP + (s * 64 + lane) * 16) = (v4u){rpt[2 * s].x, rpt[2 * s].y, rpt[2 * s + 1].x, rpt[2 * s + 1].y};
;         }
; #pragma unroll
;         for (int it = 0; it < 4; ++it) {
;             const v2u Qv = tr16(ir + 3 * IMG + 32 * it);
;             *(v2u*)(rec + REC_VV + (it * 64 + lane) * 8) = Qv;
;         }
	v_cvt_pk_bf16_f32 v0, v80, s0
	v_cvt_pk_bf16_f32 v88, v81, s0
	v_cvt_pk_bf16_f32 v89, v82, s0
	v_cvt_pk_bf16_f32 v90, v83, s0
	v_perm_b32 v89, v90, v89, s0
	v_perm_b32 v88, v88, v0, s0
	s_nop 1
	v_mfma_f32_16x16x16_bf16 v[80:83], v[98:99], v[88:89], v[80:83]
	s_nop 7
	v_cvt_pk_bf16_f32 v0, v80, s0
	v_cvt_pk_bf16_f32 v88, v81, s0
	v_cvt_pk_bf16_f32 v89, v82, s0
	v_cvt_pk_bf16_f32 v90, v83, s0
	v_perm_b32 v89, v90, v89, s0
	v_perm_b32 v88, v88, v0, s0
	s_nop 1
	v_mfma_f32_16x16x16_bf16 v[80:83], v[92:93], v[88:89], v[80:83]
	s_nop 7
	v_cvt_pk_bf16_f32 v0, v80, s0
	v_cvt_pk_bf16_f32 v88, v81, s0
	v_cvt_pk_bf16_f32 v89, v82, s0
	v_cvt_pk_bf16_f32 v90, v83, s0
	v_perm_b32 v89, v90, v89, s0
	v_perm_b32 v88, v88, v0, s0
	v_cvt_pk_bf16_f32 v0, v84, s0
	v_cvt_pk_bf16_f32 v84, v85, s0
	v_mfma_f32_16x16x16_bf16 v[80:83], v[2:3], v[88:89], v[80:83]
	v_perm_b32 v3, v103, v102, s0
	v_perm_b32 v2, v101, v100, s0
	v_cvt_pk_bf16_f32 v85, v86, s0
	v_cvt_pk_bf16_f32 v86, v87, s0
	v_perm_b32 v85, v86, v85, s0
	v_perm_b32 v84, v84, v0, s0
	s_nop 1
	v_cvt_pk_bf16_f32 v87, v80, s0
	v_cvt_pk_bf16_f32 v90, v81, s0
	v_cvt_pk_bf16_f32 v91, v82, s0
	v_cvt_pk_bf16_f32 v92, v83, s0
	v_mfma_f32_16x16x16_bf16 v[80:83], v[2:3], v[84:85], 0
	v_lshlrev_b32_e32 v86, 4, v164
	v_lshrrev_b32_e32 v0, 2, v166
	v_or_b32_e32 v0, v165, v0
	s_nop 4
	v_cvt_pk_bf16_f32 v89, v82, v83
	v_perm_b32 v83, v92, v91, s0
	v_perm_b32 v82, v90, v87, s0
	v_ashrrev_i32_e32 v87, 31, v86
	v_cvt_pk_bf16_f32 v88, v80, v81
	v_mfma_f32_16x16x16_bf16 v[76:79], v[2:3], v[82:83], v[76:79]
	v_lshl_add_u64 v[80:81], s[4:5], 0, v[86:87]
	v_add_co_u32_e32 v2, vcc, s14, v80
	s_movk_i32 s0, 0x90
	s_nop 0
	v_addc_co_u32_e32 v3, vcc, 0, v81, vcc
	s_nop 2
	v_cvt_pk_bf16_f32 v91, v78, v79
	v_cvt_pk_bf16_f32 v90, v76, v77
	global_store_dwordx4 v[2:3], v[88:91], off offset:2048 nt
	v_lshlrev_b32_e32 v2, 3, v164
	v_mul_lo_u32 v0, v0, s0
	v_and_b32_e32 v3, 24, v2
	v_add3_u32 v0, s13, v0, v3
	ds_read_b64_tr_b16 v[78:79], v0
	ds_read_b64_tr_b16 v[88:89], v0 offset:2304
	ds_read_b64_tr_b16 v[90:91], v0 offset:4608
	s_waitcnt lgkmcnt(2)
	v_mfma_f32_16x16x16_bf16 v[92:95], v[78:79], v[84:85], 0
	s_add_u32 s0, s4, 0x1000
	s_addc_u32 s1, s5, 0
	v_ashrrev_i32_e32 v3, 31, v2
	s_nop 4
	v_cvt_pk_bf16_f32 v77, v94, v95
	v_cvt_pk_bf16_f32 v76, v92, v93
	v_mfma_f32_16x16x16_bf16 v[92:95], v[78:79], v[82:83], v[72:75]
	s_nop 2
	v_lshl_add_u64 v[74:75], s[0:1], 0, v[86:87]
	s_waitcnt lgkmcnt(0)
	global_store_dwordx4 v[74:75], v[88:91], off nt
	ds_read_b64_tr_b16 v[74:75], v0 offset:32
	ds_read_b64_tr_b16 v[88:89], v0 offset:2336
	ds_read_b64_tr_b16 v[90:91], v0 offset:4640
	s_waitcnt lgkmcnt(2)
	v_mfma_f32_16x16x16_bf16 v[68:71], v[74:75], v[82:83], v[68:71]
	v_cvt_pk_bf16_f32 v73, v94, v95
	v_cvt_pk_bf16_f32 v72, v92, v93
	v_mfma_f32_16x16x16_bf16 v[92:95], v[74:75], v[84:85], 0
	s_nop 4
	v_cvt_pk_bf16_f32 v74, v68, v69
	v_add_u32_e32 v68, 0x400, v86
	v_ashrrev_i32_e32 v69, 31, v68
	v_cvt_pk_bf16_f32 v75, v70, v71
	v_lshl_add_u64 v[70:71], s[0:1], 0, v[68:69]
	s_waitcnt lgkmcnt(0)
	global_store_dwordx4 v[70:71], v[88:91], off nt
	ds_read_b64_tr_b16 v[70:71], v0 offset:64
	ds_read_b64_tr_b16 v[88:89], v0 offset:2368
	ds_read_b64_tr_b16 v[90:91], v0 offset:4672
	s_waitcnt lgkmcnt(2)
	v_mfma_f32_16x16x16_bf16 v[64:67], v[70:71], v[82:83], v[64:67]
	v_cvt_pk_bf16_f32 v79, v94, v95
	v_cvt_pk_bf16_f32 v78, v92, v93
	v_mfma_f32_16x16x16_bf16 v[92:95], v[70:71], v[84:85], 0
	s_nop 4
	v_cvt_pk_bf16_f32 v98, v64, v65
	v_add_u32_e32 v64, 0x800, v86
	v_ashrrev_i32_e32 v65, 31, v64
	v_lshl_add_u64 v[64:65], s[0:1], 0, v[64:65]
	s_waitcnt lgkmcnt(0)
	global_store_dwordx4 v[64:65], v[88:91], off nt
	v_cvt_pk_bf16_f32 v99, v66, v67
	ds_read_b64_tr_b16 v[70:71], v0 offset:96
	ds_read_b64_tr_b16 v[64:65], v0 offset:2400
	ds_read_b64_tr_b16 v[66:67], v0 offset:4704
	s_waitcnt lgkmcnt(2)
	v_mfma_f32_16x16x16_bf16 v[60:63], v[70:71], v[82:83], v[60:63]
	v_cvt_pk_bf16_f32 v95, v94, v95
	v_cvt_pk_bf16_f32 v94, v92, v93
	v_mfma_f32_16x16x16_bf16 v[88:91], v[70:71], v[84:85], 0
	s_nop 4
	v_cvt_pk_bf16_f32 v100, v60, v61
	v_add_u32_e32 v60, 0xc00, v86
	v_ashrrev_i32_e32 v61, 31, v60
	v_lshl_add_u64 v[60:61], s[0:1], 0, v[60:61]
	v_cvt_pk_bf16_f32 v101, v62, v63
	v_cvt_pk_bf16_f32 v97, v90, v91
	v_cvt_pk_bf16_f32 v96, v88, v89
	s_waitcnt lgkmcnt(0)
	global_store_dwordx4 v[60:61], v[64:67], off nt
	global_store_dwordx4 v[80:81], v[76:79], off nt
	global_store_dwordx4 v[80:81], v[72:75], off offset:2048 nt
	global_store_dwordx4 v[80:81], v[94:97], off offset:1024 nt
	global_store_dwordx4 v[80:81], v[98:101], off offset:3072 nt
	ds_read_b64_tr_b16 v[60:61], v0 offset:6912
	s_add_u32 s0, s4, 0x2000
	s_addc_u32 s1, s5, 0
	v_lshl_add_u64 v[62:63], s[0:1], 0, v[2:3]
	s_add_i32 s18, s18, s19
	s_waitcnt lgkmcnt(0)
	global_store_dwordx2 v[62:63], v[60:61], off nt
	ds_read_b64_tr_b16 v[60:61], v0 offset:6944
	v_add_u32_e32 v62, 0x200, v2
	v_ashrrev_i32_e32 v63, 31, v62
	v_lshl_add_u64 v[62:63], s[0:1], 0, v[62:63]
	s_and_b64 vcc, exec, s[10:11]
	s_waitcnt lgkmcnt(0)
	global_store_dwordx2 v[62:63], v[60:61], off nt
	ds_read_b64_tr_b16 v[60:61], v0 offset:6976
	v_sub_u32_e32 v62, v68, v2
	v_ashrrev_i32_e32 v63, 31, v62
	v_lshl_add_u64 v[62:63], s[0:1], 0, v[62:63]
	v_add_u32_e32 v2, 0x600, v2
	s_waitcnt lgkmcnt(0)
	global_store_dwordx2 v[62:63], v[60:61], off nt
	ds_read_b64_tr_b16 v[60:61], v0 offset:7008
	v_ashrrev_i32_e32 v3, 31, v2
	v_lshl_add_u64 v[2:3], s[0:1], 0, v[2:3]
	s_waitcnt lgkmcnt(0)
	global_store_dwordx2 v[2:3], v[60:61], off nt
	s_cbranch_vccnz .LBB0_218

; __device__ __forceinline__ void ph_wkv1(const Params& p, int jl, LAS unsigned char* lds, int lane_in, int wave) {
;     ...
;         if (vres) {
; #pragma unroll
;             for (int P = 0; P < 2; ++P) { const auto t0 = __builtin_amdgcn_permlane16_swap(pvp[2 * P].x, pvp[2 * P + 1].x, false, false), t1 = __builtin_amdgcn_permlane16_swap(pvp[2 * P].y, pvp[2 * P + 1].y, false, false);
;                 *(v4u*)(VP + (size_t)(r0 + fr) * D + h * WN + (fq & 1) * 16 + (fq >> 1) * 8 + 32 * P) = (v4u){t0[0], t1[0], t0[1], t1[1]}; }
;         }
; #pragma unroll
;         for (int jt = 0; jt < 4; ++jt) if (fr == 15) *(f32x4*)(rec + REC_GC + (16 * jt + 4 * fq) * 4) = ggv[jt];
.LBB0_211:
	s_lshr_b32 s25, s24, 4
	s_mulk_i32 s25, 0x810
	v_or_b32_e32 v0, s25, v166
	s_mulk_i32 s24, 0x810
	v_subrev_u32_e32 v0, s24, v0
	v_add_u32_e32 v2, s18, v0
	v_ashrrev_i32_e32 v3, 31, v2
	s_and_b64 vcc, exec, s[0:1]
	s_cbranch_vccz .LBB0_214
	s_and_b64 vcc, exec, s[4:5]
	s_cbranch_vccnz .LBB0_214
	v_readlane_b32 s0, v254, 51
	v_lshlrev_b64 v[88:89], 11, v[2:3]
	v_readlane_b32 s1, v254, 52
	s_lshl_b32 s94, s23, 1
	v_and_b32_e32 v0, 16, v164
	v_lshl_add_u64 v[88:89], s[0:1], 0, v[88:89]
	v_lshl_add_u64 v[88:89], v[88:89], 0, s[94:95]
	v_lshlrev_b32_e32 v0, 1, v0
	v_lshl_add_u64 v[88:89], v[88:89], 0, v[0:1]
	v_ashrrev_i32_e32 v0, 2, v164
	v_and_b32_e32 v90, -8, v0
	v_ashrrev_i32_e32 v91, 31, v90
	v_lshl_add_u64 v[88:89], v[90:91], 1, v[88:89]
	v_permlane16_swap_b32_e32 v100, v102
	v_permlane16_swap_b32_e32 v101, v103
	v_permlane16_swap_b32_e32 v116, v118
	v_permlane16_swap_b32_e32 v117, v119
	global_store_dwordx4 v[88:89], v[100:103], off nt
	global_store_dwordx4 v[88:89], v[116:119], off offset:64 nt
.LBB0_214:
	v_exp_f32_e64 v88, -v92
	v_exp_f32_e64 v89, -v93
	v_exp_f32_e64 v90, -v94
	v_exp_f32_e64 v91, -v95
	v_exp_f32_e64 v92, -v152
	v_exp_f32_e64 v93, -v148
	v_exp_f32_e64 v94, -v144
	v_exp_f32_e64 v95, -v145
	v_exp_f32_e64 v96, -v163
	v_exp_f32_e64 v97, -v154
	v_exp_f32_e64 v98, -v150
	v_exp_f32_e64 v99, -v151
	v_exp_f32_e64 v100, -v177
	v_exp_f32_e64 v101, -v162
	v_exp_f32_e64 v102, -v160
	v_exp_f32_e64 v103, -v161
	s_mul_i32 s1, s20, 0x2d00
	v_readlane_b32 s4, v252, 47
	s_mul_hi_i32 s0, s20, 0x2d00
	s_add_u32 s4, s4, s1
	v_readlane_b32 s1, v252, 48
	s_addc_u32 s5, s1, s0
	v_cmp_eq_u32_e32 vcc, 15, v166
	s_and_saveexec_b64 s[0:1], vcc
	s_cbranch_execz .LBB0_216
	v_and_b32_e32 v116, -16, v164
	s_add_u32 s24, s4, 0x2c00
	s_addc_u32 s25, s5, 0
	v_ashrrev_i32_e32 v117, 31, v116
	v_lshl_add_u64 v[118:119], s[24:25], 0, v[116:117]
	global_store_dwordx4 v[118:119], v[100:103], off nt
	v_add_u32_e32 v118, 64, v116
	v_ashrrev_i32_e32 v119, 31, v118
	v_lshl_add_u64 v[118:119], s[24:25], 0, v[118:119]
	global_store_dwordx4 v[118:119], v[96:99], off nt
	v_add_u32_e32 v118, 0x80, v116
	v_add_u32_e32 v116, 0xc0, v116
	v_ashrrev_i32_e32 v119, 31, v118
	v_ashrrev_i32_e32 v117, 31, v116
	v_lshl_add_u64 v[118:119], s[24:25], 0, v[118:119]
	v_lshl_add_u64 v[116:117], s[24:25], 0, v[116:117]
	global_store_dwordx4 v[118:119], v[92:95], off nt
	global_store_dwordx4 v[116:117], v[88:91], off nt
